# proj epilogue: vt8 fp8 bytes transposed within lane quads (DPP quad_perm + v_perm) and stored as 2 dwords instead of 8 byte stores
# speedup vs baseline: 1.0170x; 1.0000x over previous
; DI unsigned pack2(float a, float b) { f2_t v = {a, b}; return __builtin_bit_cast(unsigned, __builtin_convertvector(v, bf2_t)); }
;   DI void operator()(const f32x4 (&acc)[2][2][4][2], const pg8::Unit& u, int wr, int wc, int fr, int fq) const {
;     ...
;           const int row = u.pm * 256 + ai * 128 + wr * 64 + m * 16 + fr;
;           f32x4 x1 = acc[ai][bj][m][0], x2 = acc[ai][bj][m][1];
;           if (mode != 0) {
;             const float pos = (float)(row & (S - 1));
; #pragma unroll
;             for (int e = 0; e < 4; ++e) {
;               const float ang = __fmul_rn(pos, invv[e]);
;               float sn, cs; sincos_big(ang, sn, cs);
;               const float y1 = x1[e] * cs - x2[e] * sn, y2 = x2[e] * cs + x1[e] * sn;
;               x1[e] = y1; x2[e] = y2;
;             }
;           }
;           u16* dp = proj + (size_t)row * NPROJ;
;           *(uint2*)(dp + c1) = make_uint2(pack2(x1[0] * scale, x1[1] * scale), pack2(x1[2] * scale, x1[3] * scale));
;           *(uint2*)(dp + c2) = make_uint2(pack2(x2[0] * scale, x2[1] * scale), pack2(x2[2] * scale, x2[3] * scale));
;           if (gcol0 >= 512 && gcol0 < 768) {
;             const int hd = (gcol0 - 512) >> 6, d0 = (gcol0 & 63) + 4 * fq;
;             unsigned char* vp = vt8 + ((size_t)((row >> 14) * 4 + hd) * 64 + d0) * S + (row & (S - 1));
;             const int w1a = __builtin_amdgcn_cvt_pk_fp8_f32(x1[0], x1[1], 0, false), w1b = __builtin_amdgcn_cvt_pk_fp8_f32(x1[2], x1[3], 0, false);
;             const int w2a = __builtin_amdgcn_cvt_pk_fp8_f32(x2[0], x2[1], 0, false), w2b = __builtin_amdgcn_cvt_pk_fp8_f32(x2[2], x2[3], 0, false);
;             vp[0] = (unsigned char)(w1a & 0xff); vp[(size_t)S] = (unsigned char)((w1a >> 8) & 0xff); vp[(size_t)2 * S] = (unsigned char)(w1b & 0xff); vp[(size_t)3 * S] = (unsigned char)((w1b >> 8) & 0xff);
;             unsigned char* vq = vp + (size_t)16 * S;
;             vq[0] = (unsigned char)(w2a & 0xff); vq[(size_t)S] = (unsigned char)((w2a >> 8) & 0xff); vq[(size_t)2 * S] = (unsigned char)(w2b & 0xff); vq[(size_t)3 * S] = (unsigned char)((w2b >> 8) & 0xff);
.LBB0_129:
	s_and_b32 s7, s20, 0xffffff40
	s_or_b32 s7, s7, s58
	s_and_b64 s[36:37], s[36:37], exec
	s_cselect_b32 s7, s7, s20
	s_cselect_b32 s21, 32, 16
	v_or_b32_e32 v174, s7, v180
	s_addk_i32 s20, 0xfe00
	s_ashr_i32 s7, s19, 12
	s_lshr_b32 s20, s20, 6
	s_and_b32 s7, s7, -4
	v_mov_b64_e32 v[168:169], s[28:29]
	v_ashrrev_i32_e32 v175, 31, v174
	s_or_b32 s36, s7, s20
	v_mad_i64_i32 v[168:169], s[42:43], v187, s9, v[168:169]
	v_pk_mul_f32 v[176:177], v[170:171], v[152:153] op_sel_hi:[0,1]
	v_pk_mul_f32 v[188:189], v[170:171], v[154:155] op_sel_hi:[0,1]
	v_or_b32_e32 v172, s21, v174
	s_ashr_i32 s37, s36, 31
	v_cvt_pk_bf16_f32 v176, v176, v177
	v_cvt_pk_bf16_f32 v177, v188, v189
	v_lshl_add_u64 v[188:189], v[174:175], 1, v[168:169]
	v_ashrrev_i32_e32 v173, 31, v172
	s_lshl_b64 s[40:41], s[36:37], 20
	v_bfe_u32 v222, v227, 4, 1
	v_mul_u32_u24_e32 v222, 0x17ff8, v222
	v_mov_b32_e32 v223, 0
	v_mov_b32_e32 v200, v176
	v_mov_b32_e32 v201, v177
	v_lshl_add_u64 v[204:205], v[188:189], 0, v[222:223]
	v_pk_mul_f32 v[176:177], v[170:171], v[148:149] op_sel_hi:[0,1]
	v_pk_mul_f32 v[188:189], v[170:171], v[150:151] op_sel_hi:[0,1]
	s_cmp_eq_u32 s18, 2
	v_cvt_pk_bf16_f32 v176, v176, v177
	v_cvt_pk_bf16_f32 v177, v188, v189
	v_lshl_add_u64 v[188:189], v[172:173], 1, v[168:169]
	s_cselect_b64 s[36:37], -1, 0
	s_cmp_lg_u32 s18, 2
	v_mov_b32_e32 v208, v176
	v_mov_b32_e32 v209, v177
	v_lshl_add_u64 v[212:213], v[188:189], 0, v[222:223]
	v_lshl_add_u64 v[176:177], v[162:163], 0, s[40:41]
	s_cbranch_scc1 .LBB0_131
	v_mov_b32_e32 v171, v1
	v_cvt_pk_fp8_f32 v171, v152, v153
	v_lshl_add_u64 v[188:189], v[176:177], 0, v[0:1]
	v_mov_b32_e32 v152, v1
	v_mov_b32_e32 v153, v1
	v_cvt_pk_fp8_f32 v152, v154, v155
	v_cvt_pk_fp8_f32 v153, v148, v149
	v_mov_b32_e32 v154, v1
	v_cvt_pk_fp8_f32 v154, v150, v151
	s_nop 0
	s_nop 0
	s_nop 0
	s_nop 1
	s_nop 0
	s_nop 1
	s_mov_b32 s98, 0x5040100
	s_mov_b32 s100, 0x40000
	s_mov_b32 s101, 0
	v_perm_b32 v214, v152, v171, s98
	v_perm_b32 v215, v154, v153, s98
	v_bfe_i32 v206, v227, 0, 1
	v_and_b32_e32 v206, 0x5050505, v206
	v_xor_b32_e32 v206, 0x6020400, v206
	v_bfe_i32 v207, v227, 1, 1
	v_and_b32_e32 v207, 0x6060606, v207
	v_xor_b32_e32 v207, 0x5040100, v207
	v_mov_b32_dpp v216, v214 quad_perm:[1,0,3,2] row_mask:0xf bank_mask:0xf
	v_mov_b32_dpp v217, v215 quad_perm:[1,0,3,2] row_mask:0xf bank_mask:0xf
	v_and_b32_e32 v220, 3, v227
	v_perm_b32 v214, v216, v214, v206
	v_perm_b32 v215, v217, v215, v206
	v_mul_u32_u24_e32 v220, 0x3fff, v220
	v_mov_b32_e32 v221, 0
	v_mov_b32_dpp v216, v214 quad_perm:[2,3,0,1] row_mask:0xf bank_mask:0xf
	v_mov_b32_dpp v217, v215 quad_perm:[2,3,0,1] row_mask:0xf bank_mask:0xf
	v_lshl_add_u64 v[218:219], v[188:189], 0, v[220:221]
	v_perm_b32 v214, v216, v214, v207
	v_perm_b32 v215, v217, v215, v207
	v_lshl_add_u64 v[220:221], v[218:219], 0, s[100:101]
	global_store_dword v[218:219], v214, off
	global_store_dword v[220:221], v215, off

; DI unsigned pack2(float a, float b) { f2_t v = {a, b}; return __builtin_bit_cast(unsigned, __builtin_convertvector(v, bf2_t)); }
;   DI void operator()(const f32x4 (&acc)[2][2][4][2], const pg8::Unit& u, int wr, int wc, int fr, int fq) const {
;     ...
;           u16* dp = proj + (size_t)row * NPROJ;
;           *(uint2*)(dp + c1) = make_uint2(pack2(x1[0] * scale, x1[1] * scale), pack2(x1[2] * scale, x1[3] * scale));
;           *(uint2*)(dp + c2) = make_uint2(pack2(x2[0] * scale, x2[1] * scale), pack2(x2[2] * scale, x2[3] * scale));
;           if (gcol0 >= 512 && gcol0 < 768) {
;             const int hd = (gcol0 - 512) >> 6, d0 = (gcol0 & 63) + 4 * fq;
;             unsigned char* vp = vt8 + ((size_t)((row >> 14) * 4 + hd) * 64 + d0) * S + (row & (S - 1));
;             const int w1a = __builtin_amdgcn_cvt_pk_fp8_f32(x1[0], x1[1], 0, false), w1b = __builtin_amdgcn_cvt_pk_fp8_f32(x1[2], x1[3], 0, false);
;             const int w2a = __builtin_amdgcn_cvt_pk_fp8_f32(x2[0], x2[1], 0, false), w2b = __builtin_amdgcn_cvt_pk_fp8_f32(x2[2], x2[3], 0, false);
;             vp[0] = (unsigned char)(w1a & 0xff); vp[(size_t)S] = (unsigned char)((w1a >> 8) & 0xff); vp[(size_t)2 * S] = (unsigned char)(w1b & 0xff); vp[(size_t)3 * S] = (unsigned char)((w1b >> 8) & 0xff);
;             unsigned char* vq = vp + (size_t)16 * S;
;             vq[0] = (unsigned char)(w2a & 0xff); vq[(size_t)S] = (unsigned char)((w2a >> 8) & 0xff); vq[(size_t)2 * S] = (unsigned char)(w2b & 0xff); vq[(size_t)3 * S] = (unsigned char)((w2b >> 8) & 0xff);
.LBB0_133:
	v_mov_b32_e32 v171, v170
	v_mov_b64_e32 v[150:151], s[28:29]
	v_mad_i64_i32 v[150:151], s[16:17], v149, s9, v[150:151]
	v_pk_mul_f32 v[154:155], v[170:171], v[144:145]
	v_pk_mul_f32 v[188:189], v[170:171], v[146:147]
	v_cvt_pk_bf16_f32 v154, v154, v155
	v_cvt_pk_bf16_f32 v155, v188, v189
	v_lshl_add_u64 v[188:189], v[174:175], 1, v[150:151]
	v_mov_b32_e32 v202, v154
	v_mov_b32_e32 v203, v155
	s_nop 1
	v_permlane16_swap_b32_e32 v200, v202
	v_permlane16_swap_b32_e32 v201, v203
	global_store_dwordx4 v[204:205], v[200:203], off
	v_pk_mul_f32 v[154:155], v[170:171], v[140:141]
	v_pk_mul_f32 v[188:189], v[170:171], v[142:143]
	v_cndmask_b32_e64 v149, 0, 1, s[36:37]
	v_cvt_pk_bf16_f32 v154, v154, v155
	v_cvt_pk_bf16_f32 v155, v188, v189
	v_lshl_add_u64 v[188:189], v[172:173], 1, v[150:151]
	v_cmp_ne_u32_e64 s[40:41], 1, v149
	s_andn2_b64 vcc, exec, s[36:37]
	v_mov_b32_e32 v210, v154
	v_mov_b32_e32 v211, v155
	s_nop 1
	v_permlane16_swap_b32_e32 v208, v210
	v_permlane16_swap_b32_e32 v209, v211
	global_store_dwordx4 v[212:213], v[208:211], off
	s_cbranch_vccnz .LBB0_135
	v_mov_b32_e32 v149, v1
	v_lshl_add_u64 v[154:155], v[176:177], 0, v[148:149]
	v_cvt_pk_fp8_f32 v149, v144, v145
	v_mov_b32_e32 v144, v1
	v_mov_b32_e32 v145, v1
	v_cvt_pk_fp8_f32 v144, v146, v147
	v_cvt_pk_fp8_f32 v145, v140, v141
	v_mov_b32_e32 v146, v1
	v_cvt_pk_fp8_f32 v146, v142, v143
	s_nop 0
	s_nop 0
	s_nop 0
	s_nop 1
	s_nop 0
	s_nop 1
	s_mov_b32 s98, 0x5040100
	s_mov_b32 s100, 0x40000
	s_mov_b32 s101, 0
	v_perm_b32 v214, v144, v149, s98
	v_perm_b32 v215, v146, v145, s98
	v_bfe_i32 v206, v227, 0, 1
	v_and_b32_e32 v206, 0x5050505, v206
	v_xor_b32_e32 v206, 0x6020400, v206
	v_bfe_i32 v207, v227, 1, 1
	v_and_b32_e32 v207, 0x6060606, v207
	v_xor_b32_e32 v207, 0x5040100, v207
	v_mov_b32_dpp v216, v214 quad_perm:[1,0,3,2] row_mask:0xf bank_mask:0xf
	v_mov_b32_dpp v217, v215 quad_perm:[1,0,3,2] row_mask:0xf bank_mask:0xf
	v_and_b32_e32 v220, 3, v227
	v_perm_b32 v214, v216, v214, v206
	v_perm_b32 v215, v217, v215, v206
	v_mul_u32_u24_e32 v220, 0x3fff, v220
	v_mov_b32_e32 v221, 0
	v_mov_b32_dpp v216, v214 quad_perm:[2,3,0,1] row_mask:0xf bank_mask:0xf
	v_mov_b32_dpp v217, v215 quad_perm:[2,3,0,1] row_mask:0xf bank_mask:0xf
	v_lshl_add_u64 v[218:219], v[154:155], 0, v[220:221]
	v_perm_b32 v214, v216, v214, v207
	v_perm_b32 v215, v217, v215, v207
	v_lshl_add_u64 v[220:221], v[218:219], 0, s[100:101]
	global_store_dword v[218:219], v214, off
	global_store_dword v[220:221], v215, off

; DI unsigned pack2(float a, float b) { f2_t v = {a, b}; return __builtin_bit_cast(unsigned, __builtin_convertvector(v, bf2_t)); }
;   DI void operator()(const f32x4 (&acc)[2][2][4][2], const pg8::Unit& u, int wr, int wc, int fr, int fq) const {
;     ...
;           u16* dp = proj + (size_t)row * NPROJ;
;           *(uint2*)(dp + c1) = make_uint2(pack2(x1[0] * scale, x1[1] * scale), pack2(x1[2] * scale, x1[3] * scale));
;           *(uint2*)(dp + c2) = make_uint2(pack2(x2[0] * scale, x2[1] * scale), pack2(x2[2] * scale, x2[3] * scale));
;           if (gcol0 >= 512 && gcol0 < 768) {
;             const int hd = (gcol0 - 512) >> 6, d0 = (gcol0 & 63) + 4 * fq;
;             unsigned char* vp = vt8 + ((size_t)((row >> 14) * 4 + hd) * 64 + d0) * S + (row & (S - 1));
;             const int w1a = __builtin_amdgcn_cvt_pk_fp8_f32(x1[0], x1[1], 0, false), w1b = __builtin_amdgcn_cvt_pk_fp8_f32(x1[2], x1[3], 0, false);
;             const int w2a = __builtin_amdgcn_cvt_pk_fp8_f32(x2[0], x2[1], 0, false), w2b = __builtin_amdgcn_cvt_pk_fp8_f32(x2[2], x2[3], 0, false);
;             vp[0] = (unsigned char)(w1a & 0xff); vp[(size_t)S] = (unsigned char)((w1a >> 8) & 0xff); vp[(size_t)2 * S] = (unsigned char)(w1b & 0xff); vp[(size_t)3 * S] = (unsigned char)((w1b >> 8) & 0xff);
;             unsigned char* vq = vp + (size_t)16 * S;
;             vq[0] = (unsigned char)(w2a & 0xff); vq[(size_t)S] = (unsigned char)((w2a >> 8) & 0xff); vq[(size_t)2 * S] = (unsigned char)(w2b & 0xff); vq[(size_t)3 * S] = (unsigned char)((w2b >> 8) & 0xff);
.LBB0_137:
	v_mov_b64_e32 v[142:143], s[28:29]
	v_mad_i64_i32 v[142:143], s[16:17], v141, s9, v[142:143]
	v_pk_mul_f32 v[146:147], v[170:171], v[136:137]
	v_pk_mul_f32 v[154:155], v[170:171], v[138:139]
	v_cvt_pk_bf16_f32 v146, v146, v147
	v_cvt_pk_bf16_f32 v147, v154, v155
	v_lshl_add_u64 v[154:155], v[174:175], 1, v[142:143]
	v_bfe_u32 v222, v227, 4, 1
	v_mul_u32_u24_e32 v222, 0x17ff8, v222
	v_mov_b32_e32 v223, 0
	v_mov_b32_e32 v200, v146
	v_mov_b32_e32 v201, v147
	v_lshl_add_u64 v[204:205], v[154:155], 0, v[222:223]
	v_pk_mul_f32 v[146:147], v[170:171], v[132:133]
	v_pk_mul_f32 v[154:155], v[170:171], v[134:135]
	v_cvt_pk_bf16_f32 v146, v146, v147
	v_cvt_pk_bf16_f32 v147, v154, v155
	v_lshl_add_u64 v[154:155], v[172:173], 1, v[142:143]
	s_and_b64 vcc, exec, s[40:41]
	v_mov_b32_e32 v208, v146
	v_mov_b32_e32 v209, v147
	v_lshl_add_u64 v[212:213], v[154:155], 0, v[222:223]
	s_cbranch_vccnz .LBB0_139
	v_mov_b32_e32 v141, v1
	v_lshl_add_u64 v[146:147], v[176:177], 0, v[140:141]
	v_cvt_pk_fp8_f32 v141, v136, v137
	v_mov_b32_e32 v136, v1
	v_mov_b32_e32 v137, v1
	v_cvt_pk_fp8_f32 v136, v138, v139
	v_cvt_pk_fp8_f32 v137, v132, v133
	v_mov_b32_e32 v138, v1
	v_cvt_pk_fp8_f32 v138, v134, v135
	s_nop 0
	s_nop 0
	s_nop 0
	s_nop 1
	s_nop 0
	s_nop 1
	s_mov_b32 s98, 0x5040100
	s_mov_b32 s100, 0x40000
	s_mov_b32 s101, 0
	v_perm_b32 v214, v136, v141, s98
	v_perm_b32 v215, v138, v137, s98
	v_bfe_i32 v206, v227, 0, 1
	v_and_b32_e32 v206, 0x5050505, v206
	v_xor_b32_e32 v206, 0x6020400, v206
	v_bfe_i32 v207, v227, 1, 1
	v_and_b32_e32 v207, 0x6060606, v207
	v_xor_b32_e32 v207, 0x5040100, v207
	v_mov_b32_dpp v216, v214 quad_perm:[1,0,3,2] row_mask:0xf bank_mask:0xf
	v_mov_b32_dpp v217, v215 quad_perm:[1,0,3,2] row_mask:0xf bank_mask:0xf
	v_and_b32_e32 v220, 3, v227
	v_perm_b32 v214, v216, v214, v206
	v_perm_b32 v215, v217, v215, v206
	v_mul_u32_u24_e32 v220, 0x3fff, v220
	v_mov_b32_e32 v221, 0
	v_mov_b32_dpp v216, v214 quad_perm:[2,3,0,1] row_mask:0xf bank_mask:0xf
	v_mov_b32_dpp v217, v215 quad_perm:[2,3,0,1] row_mask:0xf bank_mask:0xf
	v_lshl_add_u64 v[218:219], v[146:147], 0, v[220:221]
	v_perm_b32 v214, v216, v214, v207
	v_perm_b32 v215, v217, v215, v207
	v_lshl_add_u64 v[220:221], v[218:219], 0, s[100:101]
	global_store_dword v[218:219], v214, off
	global_store_dword v[220:221], v215, off

; DI unsigned pack2(float a, float b) { f2_t v = {a, b}; return __builtin_bit_cast(unsigned, __builtin_convertvector(v, bf2_t)); }
;   DI void operator()(const f32x4 (&acc)[2][2][4][2], const pg8::Unit& u, int wr, int wc, int fr, int fq) const {
;     ...
;           u16* dp = proj + (size_t)row * NPROJ;
;           *(uint2*)(dp + c1) = make_uint2(pack2(x1[0] * scale, x1[1] * scale), pack2(x1[2] * scale, x1[3] * scale));
;           *(uint2*)(dp + c2) = make_uint2(pack2(x2[0] * scale, x2[1] * scale), pack2(x2[2] * scale, x2[3] * scale));
;           if (gcol0 >= 512 && gcol0 < 768) {
;             const int hd = (gcol0 - 512) >> 6, d0 = (gcol0 & 63) + 4 * fq;
;             unsigned char* vp = vt8 + ((size_t)((row >> 14) * 4 + hd) * 64 + d0) * S + (row & (S - 1));
;             const int w1a = __builtin_amdgcn_cvt_pk_fp8_f32(x1[0], x1[1], 0, false), w1b = __builtin_amdgcn_cvt_pk_fp8_f32(x1[2], x1[3], 0, false);
;             const int w2a = __builtin_amdgcn_cvt_pk_fp8_f32(x2[0], x2[1], 0, false), w2b = __builtin_amdgcn_cvt_pk_fp8_f32(x2[2], x2[3], 0, false);
;             vp[0] = (unsigned char)(w1a & 0xff); vp[(size_t)S] = (unsigned char)((w1a >> 8) & 0xff); vp[(size_t)2 * S] = (unsigned char)(w1b & 0xff); vp[(size_t)3 * S] = (unsigned char)((w1b >> 8) & 0xff);
;             unsigned char* vq = vp + (size_t)16 * S;
;             vq[0] = (unsigned char)(w2a & 0xff); vq[(size_t)S] = (unsigned char)((w2a >> 8) & 0xff); vq[(size_t)2 * S] = (unsigned char)(w2b & 0xff); vq[(size_t)3 * S] = (unsigned char)((w2b >> 8) & 0xff);
.LBB0_141:
	v_mov_b64_e32 v[134:135], s[28:29]
	v_mad_i64_i32 v[134:135], s[16:17], v133, s9, v[134:135]
	v_pk_mul_f32 v[138:139], v[170:171], v[128:129]
	v_pk_mul_f32 v[146:147], v[170:171], v[130:131]
	v_cvt_pk_bf16_f32 v138, v138, v139
	v_cvt_pk_bf16_f32 v139, v146, v147
	v_lshl_add_u64 v[146:147], v[174:175], 1, v[134:135]
	v_mov_b32_e32 v202, v138
	v_mov_b32_e32 v203, v139
	s_nop 1
	v_permlane16_swap_b32_e32 v200, v202
	v_permlane16_swap_b32_e32 v201, v203
	global_store_dwordx4 v[204:205], v[200:203], off
	v_pk_mul_f32 v[138:139], v[170:171], v[124:125]
	v_pk_mul_f32 v[146:147], v[170:171], v[126:127]
	v_cvt_pk_bf16_f32 v138, v138, v139
	v_cvt_pk_bf16_f32 v139, v146, v147
	v_lshl_add_u64 v[146:147], v[172:173], 1, v[134:135]
	s_and_b64 vcc, exec, s[40:41]
	v_mov_b32_e32 v210, v138
	v_mov_b32_e32 v211, v139
	s_nop 1
	v_permlane16_swap_b32_e32 v208, v210
	v_permlane16_swap_b32_e32 v209, v211
	global_store_dwordx4 v[212:213], v[208:211], off
	s_cbranch_vccnz .LBB0_143
	v_mov_b32_e32 v133, v1
	v_lshl_add_u64 v[138:139], v[176:177], 0, v[132:133]
	v_cvt_pk_fp8_f32 v133, v128, v129
	v_mov_b32_e32 v128, v1
	v_mov_b32_e32 v129, v1
	v_cvt_pk_fp8_f32 v128, v130, v131
	v_cvt_pk_fp8_f32 v129, v124, v125
	v_mov_b32_e32 v130, v1
	v_cvt_pk_fp8_f32 v130, v126, v127
	s_nop 0
	s_nop 0
	s_nop 0
	s_nop 1
	s_nop 0
	s_nop 1
	s_mov_b32 s98, 0x5040100
	s_mov_b32 s100, 0x40000
	s_mov_b32 s101, 0
	v_perm_b32 v214, v128, v133, s98
	v_perm_b32 v215, v130, v129, s98
	v_bfe_i32 v206, v227, 0, 1
	v_and_b32_e32 v206, 0x5050505, v206
	v_xor_b32_e32 v206, 0x6020400, v206
	v_bfe_i32 v207, v227, 1, 1
	v_and_b32_e32 v207, 0x6060606, v207
	v_xor_b32_e32 v207, 0x5040100, v207
	v_mov_b32_dpp v216, v214 quad_perm:[1,0,3,2] row_mask:0xf bank_mask:0xf
	v_mov_b32_dpp v217, v215 quad_perm:[1,0,3,2] row_mask:0xf bank_mask:0xf
	v_and_b32_e32 v220, 3, v227
	v_perm_b32 v214, v216, v214, v206
	v_perm_b32 v215, v217, v215, v206
	v_mul_u32_u24_e32 v220, 0x3fff, v220
	v_mov_b32_e32 v221, 0
	v_mov_b32_dpp v216, v214 quad_perm:[2,3,0,1] row_mask:0xf bank_mask:0xf
	v_mov_b32_dpp v217, v215 quad_perm:[2,3,0,1] row_mask:0xf bank_mask:0xf
	v_lshl_add_u64 v[218:219], v[138:139], 0, v[220:221]
	v_perm_b32 v214, v216, v214, v207
	v_perm_b32 v215, v217, v215, v207
	v_lshl_add_u64 v[220:221], v[218:219], 0, s[100:101]
	global_store_dword v[218:219], v214, off
	global_store_dword v[220:221], v215, off

; DI unsigned pack2(float a, float b) { f2_t v = {a, b}; return __builtin_bit_cast(unsigned, __builtin_convertvector(v, bf2_t)); }
;   DI void operator()(const f32x4 (&acc)[2][2][4][2], const pg8::Unit& u, int wr, int wc, int fr, int fq) const {
;     ...
;           const int row = u.pm * 256 + ai * 128 + wr * 64 + m * 16 + fr;
;           f32x4 x1 = acc[ai][bj][m][0], x2 = acc[ai][bj][m][1];
;           if (mode != 0) {
;             const float pos = (float)(row & (S - 1));
; #pragma unroll
;             for (int e = 0; e < 4; ++e) {
;               const float ang = __fmul_rn(pos, invv[e]);
;               float sn, cs; sincos_big(ang, sn, cs);
;               const float y1 = x1[e] * cs - x2[e] * sn, y2 = x2[e] * cs + x1[e] * sn;
;               x1[e] = y1; x2[e] = y2;
;             }
;           }
;           u16* dp = proj + (size_t)row * NPROJ;
;           *(uint2*)(dp + c1) = make_uint2(pack2(x1[0] * scale, x1[1] * scale), pack2(x1[2] * scale, x1[3] * scale));
;           *(uint2*)(dp + c2) = make_uint2(pack2(x2[0] * scale, x2[1] * scale), pack2(x2[2] * scale, x2[3] * scale));
;           if (gcol0 >= 512 && gcol0 < 768) {
;             const int hd = (gcol0 - 512) >> 6, d0 = (gcol0 & 63) + 4 * fq;
;             unsigned char* vp = vt8 + ((size_t)((row >> 14) * 4 + hd) * 64 + d0) * S + (row & (S - 1));
;             const int w1a = __builtin_amdgcn_cvt_pk_fp8_f32(x1[0], x1[1], 0, false), w1b = __builtin_amdgcn_cvt_pk_fp8_f32(x1[2], x1[3], 0, false);
;             const int w2a = __builtin_amdgcn_cvt_pk_fp8_f32(x2[0], x2[1], 0, false), w2b = __builtin_amdgcn_cvt_pk_fp8_f32(x2[2], x2[3], 0, false);
;             vp[0] = (unsigned char)(w1a & 0xff); vp[(size_t)S] = (unsigned char)((w1a >> 8) & 0xff); vp[(size_t)2 * S] = (unsigned char)(w1b & 0xff); vp[(size_t)3 * S] = (unsigned char)((w1b >> 8) & 0xff);
;             unsigned char* vq = vp + (size_t)16 * S;
;             vq[0] = (unsigned char)(w2a & 0xff); vq[(size_t)S] = (unsigned char)((w2a >> 8) & 0xff); vq[(size_t)2 * S] = (unsigned char)(w2b & 0xff); vq[(size_t)3 * S] = (unsigned char)((w2b >> 8) & 0xff);
.LBB0_145:
	s_ashr_i32 s16, s19, 12
	s_and_b32 s18, s16, -4
	v_mov_b64_e32 v[126:127], s[28:29]
	s_or_b32 s16, s18, s20
	v_mad_i64_i32 v[126:127], s[20:21], v131, s9, v[126:127]
	v_pk_mul_f32 v[128:129], v[170:171], v[120:121]
	v_pk_mul_f32 v[138:139], v[170:171], v[122:123]
	v_cvt_pk_bf16_f32 v128, v128, v129
	v_cvt_pk_bf16_f32 v129, v138, v139
	v_lshl_add_u64 v[138:139], v[174:175], 1, v[126:127]
	s_ashr_i32 s17, s16, 31
	v_bfe_u32 v222, v227, 4, 1
	v_mul_u32_u24_e32 v222, 0x17ff8, v222
	v_mov_b32_e32 v223, 0
	v_mov_b32_e32 v200, v128
	v_mov_b32_e32 v201, v129
	v_lshl_add_u64 v[204:205], v[138:139], 0, v[222:223]
	v_pk_mul_f32 v[128:129], v[170:171], v[116:117]
	v_pk_mul_f32 v[138:139], v[170:171], v[118:119]
	s_lshl_b64 s[16:17], s[16:17], 20
	v_cvt_pk_bf16_f32 v128, v128, v129
	v_cvt_pk_bf16_f32 v129, v138, v139
	v_lshl_add_u64 v[138:139], v[172:173], 1, v[126:127]
	v_mov_b32_e32 v208, v128
	v_mov_b32_e32 v209, v129
	v_lshl_add_u64 v[212:213], v[138:139], 0, v[222:223]
	s_and_b64 vcc, exec, s[40:41]
	v_lshl_add_u64 v[128:129], v[162:163], 0, s[16:17]
	s_cbranch_vccnz .LBB0_147
	v_mov_b32_e32 v125, v1
	v_lshl_add_u64 v[138:139], v[128:129], 0, v[124:125]
	v_cvt_pk_fp8_f32 v125, v120, v121
	v_mov_b32_e32 v120, v1
	v_mov_b32_e32 v121, v1
	v_cvt_pk_fp8_f32 v120, v122, v123
	v_cvt_pk_fp8_f32 v121, v116, v117
	v_mov_b32_e32 v122, v1
	v_cvt_pk_fp8_f32 v122, v118, v119
	s_nop 0
	s_nop 0
	s_nop 0
	s_nop 1
	s_nop 0
	s_nop 1
	s_mov_b32 s98, 0x5040100
	s_mov_b32 s100, 0x40000
	s_mov_b32 s101, 0
	v_perm_b32 v214, v120, v125, s98
	v_perm_b32 v215, v122, v121, s98
	v_bfe_i32 v206, v227, 0, 1
	v_and_b32_e32 v206, 0x5050505, v206
	v_xor_b32_e32 v206, 0x6020400, v206
	v_bfe_i32 v207, v227, 1, 1
	v_and_b32_e32 v207, 0x6060606, v207
	v_xor_b32_e32 v207, 0x5040100, v207
	v_mov_b32_dpp v216, v214 quad_perm:[1,0,3,2] row_mask:0xf bank_mask:0xf
	v_mov_b32_dpp v217, v215 quad_perm:[1,0,3,2] row_mask:0xf bank_mask:0xf
	v_and_b32_e32 v220, 3, v227
	v_perm_b32 v214, v216, v214, v206
	v_perm_b32 v215, v217, v215, v206
	v_mul_u32_u24_e32 v220, 0x3fff, v220
	v_mov_b32_e32 v221, 0
	v_mov_b32_dpp v216, v214 quad_perm:[2,3,0,1] row_mask:0xf bank_mask:0xf
	v_mov_b32_dpp v217, v215 quad_perm:[2,3,0,1] row_mask:0xf bank_mask:0xf
	v_lshl_add_u64 v[218:219], v[138:139], 0, v[220:221]
	v_perm_b32 v214, v216, v214, v207
	v_perm_b32 v215, v217, v215, v207
	v_lshl_add_u64 v[220:221], v[218:219], 0, s[100:101]
	global_store_dword v[218:219], v214, off
	global_store_dword v[220:221], v215, off

; DI unsigned pack2(float a, float b) { f2_t v = {a, b}; return __builtin_bit_cast(unsigned, __builtin_convertvector(v, bf2_t)); }
;   DI void operator()(const f32x4 (&acc)[2][2][4][2], const pg8::Unit& u, int wr, int wc, int fr, int fq) const {
;     ...
;           u16* dp = proj + (size_t)row * NPROJ;
;           *(uint2*)(dp + c1) = make_uint2(pack2(x1[0] * scale, x1[1] * scale), pack2(x1[2] * scale, x1[3] * scale));
;           *(uint2*)(dp + c2) = make_uint2(pack2(x2[0] * scale, x2[1] * scale), pack2(x2[2] * scale, x2[3] * scale));
;           if (gcol0 >= 512 && gcol0 < 768) {
;             const int hd = (gcol0 - 512) >> 6, d0 = (gcol0 & 63) + 4 * fq;
;             unsigned char* vp = vt8 + ((size_t)((row >> 14) * 4 + hd) * 64 + d0) * S + (row & (S - 1));
;             const int w1a = __builtin_amdgcn_cvt_pk_fp8_f32(x1[0], x1[1], 0, false), w1b = __builtin_amdgcn_cvt_pk_fp8_f32(x1[2], x1[3], 0, false);
;             const int w2a = __builtin_amdgcn_cvt_pk_fp8_f32(x2[0], x2[1], 0, false), w2b = __builtin_amdgcn_cvt_pk_fp8_f32(x2[2], x2[3], 0, false);
;             vp[0] = (unsigned char)(w1a & 0xff); vp[(size_t)S] = (unsigned char)((w1a >> 8) & 0xff); vp[(size_t)2 * S] = (unsigned char)(w1b & 0xff); vp[(size_t)3 * S] = (unsigned char)((w1b >> 8) & 0xff);
;             unsigned char* vq = vp + (size_t)16 * S;
;             vq[0] = (unsigned char)(w2a & 0xff); vq[(size_t)S] = (unsigned char)((w2a >> 8) & 0xff); vq[(size_t)2 * S] = (unsigned char)(w2b & 0xff); vq[(size_t)3 * S] = (unsigned char)((w2b >> 8) & 0xff);
.LBB0_149:
	v_mov_b64_e32 v[118:119], s[28:29]
	v_mad_i64_i32 v[118:119], s[16:17], v117, s9, v[118:119]
	v_pk_mul_f32 v[122:123], v[170:171], v[104:105]
	v_pk_mul_f32 v[138:139], v[170:171], v[106:107]
	v_cvt_pk_bf16_f32 v122, v122, v123
	v_cvt_pk_bf16_f32 v123, v138, v139
	v_lshl_add_u64 v[138:139], v[174:175], 1, v[118:119]
	v_mov_b32_e32 v202, v122
	v_mov_b32_e32 v203, v123
	s_nop 1
	v_permlane16_swap_b32_e32 v200, v202
	v_permlane16_swap_b32_e32 v201, v203
	global_store_dwordx4 v[204:205], v[200:203], off
	v_pk_mul_f32 v[122:123], v[170:171], v[100:101]
	v_pk_mul_f32 v[138:139], v[170:171], v[102:103]
	v_cvt_pk_bf16_f32 v122, v122, v123
	v_cvt_pk_bf16_f32 v123, v138, v139
	v_lshl_add_u64 v[138:139], v[172:173], 1, v[118:119]
	s_and_b64 vcc, exec, s[40:41]
	v_mov_b32_e32 v210, v122
	v_mov_b32_e32 v211, v123
	s_nop 1
	v_permlane16_swap_b32_e32 v208, v210
	v_permlane16_swap_b32_e32 v209, v211
	global_store_dwordx4 v[212:213], v[208:211], off
	s_cbranch_vccnz .LBB0_151
	v_mov_b32_e32 v117, v1
	v_lshl_add_u64 v[122:123], v[128:129], 0, v[116:117]
	v_cvt_pk_fp8_f32 v117, v104, v105
	v_mov_b32_e32 v104, v1
	v_mov_b32_e32 v105, v1
	v_cvt_pk_fp8_f32 v104, v106, v107
	v_cvt_pk_fp8_f32 v105, v100, v101
	v_mov_b32_e32 v106, v1
	v_cvt_pk_fp8_f32 v106, v102, v103
	s_nop 0
	s_nop 0
	s_nop 0
	s_nop 1
	s_nop 0
	s_nop 1
	s_mov_b32 s98, 0x5040100
	s_mov_b32 s100, 0x40000
	s_mov_b32 s101, 0
	v_perm_b32 v214, v104, v117, s98
	v_perm_b32 v215, v106, v105, s98
	v_bfe_i32 v206, v227, 0, 1
	v_and_b32_e32 v206, 0x5050505, v206
	v_xor_b32_e32 v206, 0x6020400, v206
	v_bfe_i32 v207, v227, 1, 1
	v_and_b32_e32 v207, 0x6060606, v207
	v_xor_b32_e32 v207, 0x5040100, v207
	v_mov_b32_dpp v216, v214 quad_perm:[1,0,3,2] row_mask:0xf bank_mask:0xf
	v_mov_b32_dpp v217, v215 quad_perm:[1,0,3,2] row_mask:0xf bank_mask:0xf
	v_and_b32_e32 v220, 3, v227
	v_perm_b32 v214, v216, v214, v206
	v_perm_b32 v215, v217, v215, v206
	v_mul_u32_u24_e32 v220, 0x3fff, v220
	v_mov_b32_e32 v221, 0
	v_mov_b32_dpp v216, v214 quad_perm:[2,3,0,1] row_mask:0xf bank_mask:0xf
	v_mov_b32_dpp v217, v215 quad_perm:[2,3,0,1] row_mask:0xf bank_mask:0xf
	v_lshl_add_u64 v[218:219], v[122:123], 0, v[220:221]
	v_perm_b32 v214, v216, v214, v207
	v_perm_b32 v215, v217, v215, v207
	v_lshl_add_u64 v[220:221], v[218:219], 0, s[100:101]
	global_store_dword v[218:219], v214, off
	global_store_dword v[220:221], v215, off

; DI unsigned pack2(float a, float b) { f2_t v = {a, b}; return __builtin_bit_cast(unsigned, __builtin_convertvector(v, bf2_t)); }
;   DI void operator()(const f32x4 (&acc)[2][2][4][2], const pg8::Unit& u, int wr, int wc, int fr, int fq) const {
;     ...
;           u16* dp = proj + (size_t)row * NPROJ;
;           *(uint2*)(dp + c1) = make_uint2(pack2(x1[0] * scale, x1[1] * scale), pack2(x1[2] * scale, x1[3] * scale));
;           *(uint2*)(dp + c2) = make_uint2(pack2(x2[0] * scale, x2[1] * scale), pack2(x2[2] * scale, x2[3] * scale));
;           if (gcol0 >= 512 && gcol0 < 768) {
;             const int hd = (gcol0 - 512) >> 6, d0 = (gcol0 & 63) + 4 * fq;
;             unsigned char* vp = vt8 + ((size_t)((row >> 14) * 4 + hd) * 64 + d0) * S + (row & (S - 1));
;             const int w1a = __builtin_amdgcn_cvt_pk_fp8_f32(x1[0], x1[1], 0, false), w1b = __builtin_amdgcn_cvt_pk_fp8_f32(x1[2], x1[3], 0, false);
;             const int w2a = __builtin_amdgcn_cvt_pk_fp8_f32(x2[0], x2[1], 0, false), w2b = __builtin_amdgcn_cvt_pk_fp8_f32(x2[2], x2[3], 0, false);
;             vp[0] = (unsigned char)(w1a & 0xff); vp[(size_t)S] = (unsigned char)((w1a >> 8) & 0xff); vp[(size_t)2 * S] = (unsigned char)(w1b & 0xff); vp[(size_t)3 * S] = (unsigned char)((w1b >> 8) & 0xff);
;             unsigned char* vq = vp + (size_t)16 * S;
;             vq[0] = (unsigned char)(w2a & 0xff); vq[(size_t)S] = (unsigned char)((w2a >> 8) & 0xff); vq[(size_t)2 * S] = (unsigned char)(w2b & 0xff); vq[(size_t)3 * S] = (unsigned char)((w2b >> 8) & 0xff);
.LBB0_153:
	v_mov_b64_e32 v[102:103], s[28:29]
	v_mad_i64_i32 v[102:103], s[16:17], v101, s9, v[102:103]
	v_pk_mul_f32 v[106:107], v[170:171], v[96:97]
	v_pk_mul_f32 v[122:123], v[170:171], v[98:99]
	v_cvt_pk_bf16_f32 v106, v106, v107
	v_cvt_pk_bf16_f32 v107, v122, v123
	v_lshl_add_u64 v[122:123], v[174:175], 1, v[102:103]
	v_bfe_u32 v222, v227, 4, 1
	v_mul_u32_u24_e32 v222, 0x17ff8, v222
	v_mov_b32_e32 v223, 0
	v_mov_b32_e32 v200, v106
	v_mov_b32_e32 v201, v107
	v_lshl_add_u64 v[204:205], v[122:123], 0, v[222:223]
	v_pk_mul_f32 v[106:107], v[170:171], v[92:93]
	v_pk_mul_f32 v[122:123], v[170:171], v[94:95]
	v_cvt_pk_bf16_f32 v106, v106, v107
	v_cvt_pk_bf16_f32 v107, v122, v123
	v_lshl_add_u64 v[122:123], v[172:173], 1, v[102:103]
	s_and_b64 vcc, exec, s[40:41]
	v_mov_b32_e32 v208, v106
	v_mov_b32_e32 v209, v107
	v_lshl_add_u64 v[212:213], v[122:123], 0, v[222:223]
	s_cbranch_vccnz .LBB0_155
	v_mov_b32_e32 v101, v1
	v_lshl_add_u64 v[106:107], v[128:129], 0, v[100:101]
	v_cvt_pk_fp8_f32 v101, v96, v97
	v_mov_b32_e32 v96, v1
	v_mov_b32_e32 v97, v1
	v_cvt_pk_fp8_f32 v96, v98, v99
	v_cvt_pk_fp8_f32 v97, v92, v93
	v_mov_b32_e32 v98, v1
	v_cvt_pk_fp8_f32 v98, v94, v95
	s_nop 0
	s_nop 0
	s_nop 0
	s_nop 1
	s_nop 0
	s_nop 1
	s_mov_b32 s98, 0x5040100
	s_mov_b32 s100, 0x40000
	s_mov_b32 s101, 0
	v_perm_b32 v214, v96, v101, s98
	v_perm_b32 v215, v98, v97, s98
	v_bfe_i32 v206, v227, 0, 1
	v_and_b32_e32 v206, 0x5050505, v206
	v_xor_b32_e32 v206, 0x6020400, v206
	v_bfe_i32 v207, v227, 1, 1
	v_and_b32_e32 v207, 0x6060606, v207
	v_xor_b32_e32 v207, 0x5040100, v207
	v_mov_b32_dpp v216, v214 quad_perm:[1,0,3,2] row_mask:0xf bank_mask:0xf
	v_mov_b32_dpp v217, v215 quad_perm:[1,0,3,2] row_mask:0xf bank_mask:0xf
	v_and_b32_e32 v220, 3, v227
	v_perm_b32 v214, v216, v214, v206
	v_perm_b32 v215, v217, v215, v206
	v_mul_u32_u24_e32 v220, 0x3fff, v220
	v_mov_b32_e32 v221, 0
	v_mov_b32_dpp v216, v214 quad_perm:[2,3,0,1] row_mask:0xf bank_mask:0xf
	v_mov_b32_dpp v217, v215 quad_perm:[2,3,0,1] row_mask:0xf bank_mask:0xf
	v_lshl_add_u64 v[218:219], v[106:107], 0, v[220:221]
	v_perm_b32 v214, v216, v214, v207
	v_perm_b32 v215, v217, v215, v207
	v_lshl_add_u64 v[220:221], v[218:219], 0, s[100:101]
	global_store_dword v[218:219], v214, off
	global_store_dword v[220:221], v215, off

; DI unsigned pack2(float a, float b) { f2_t v = {a, b}; return __builtin_bit_cast(unsigned, __builtin_convertvector(v, bf2_t)); }
;   DI void operator()(const f32x4 (&acc)[2][2][4][2], const pg8::Unit& u, int wr, int wc, int fr, int fq) const {
;     ...
;           u16* dp = proj + (size_t)row * NPROJ;
;           *(uint2*)(dp + c1) = make_uint2(pack2(x1[0] * scale, x1[1] * scale), pack2(x1[2] * scale, x1[3] * scale));
;           *(uint2*)(dp + c2) = make_uint2(pack2(x2[0] * scale, x2[1] * scale), pack2(x2[2] * scale, x2[3] * scale));
;           if (gcol0 >= 512 && gcol0 < 768) {
;             const int hd = (gcol0 - 512) >> 6, d0 = (gcol0 & 63) + 4 * fq;
;             unsigned char* vp = vt8 + ((size_t)((row >> 14) * 4 + hd) * 64 + d0) * S + (row & (S - 1));
;             const int w1a = __builtin_amdgcn_cvt_pk_fp8_f32(x1[0], x1[1], 0, false), w1b = __builtin_amdgcn_cvt_pk_fp8_f32(x1[2], x1[3], 0, false);
;             const int w2a = __builtin_amdgcn_cvt_pk_fp8_f32(x2[0], x2[1], 0, false), w2b = __builtin_amdgcn_cvt_pk_fp8_f32(x2[2], x2[3], 0, false);
;             vp[0] = (unsigned char)(w1a & 0xff); vp[(size_t)S] = (unsigned char)((w1a >> 8) & 0xff); vp[(size_t)2 * S] = (unsigned char)(w1b & 0xff); vp[(size_t)3 * S] = (unsigned char)((w1b >> 8) & 0xff);
;             unsigned char* vq = vp + (size_t)16 * S;
;             vq[0] = (unsigned char)(w2a & 0xff); vq[(size_t)S] = (unsigned char)((w2a >> 8) & 0xff); vq[(size_t)2 * S] = (unsigned char)(w2b & 0xff); vq[(size_t)3 * S] = (unsigned char)((w2b >> 8) & 0xff);
.LBB0_157:
	v_mov_b64_e32 v[94:95], s[28:29]
	v_mad_i64_i32 v[94:95], s[16:17], v93, s9, v[94:95]
	v_pk_mul_f32 v[98:99], v[170:171], v[88:89]
	v_pk_mul_f32 v[106:107], v[170:171], v[90:91]
	v_cvt_pk_bf16_f32 v98, v98, v99
	v_cvt_pk_bf16_f32 v99, v106, v107
	v_lshl_add_u64 v[106:107], v[174:175], 1, v[94:95]
	v_mov_b32_e32 v202, v98
	v_mov_b32_e32 v203, v99
	s_nop 1
	v_permlane16_swap_b32_e32 v200, v202
	v_permlane16_swap_b32_e32 v201, v203
	global_store_dwordx4 v[204:205], v[200:203], off
	v_pk_mul_f32 v[98:99], v[170:171], v[84:85]
	v_pk_mul_f32 v[106:107], v[170:171], v[86:87]
	v_cvt_pk_bf16_f32 v98, v98, v99
	v_cvt_pk_bf16_f32 v99, v106, v107
	v_lshl_add_u64 v[106:107], v[172:173], 1, v[94:95]
	s_and_b64 vcc, exec, s[40:41]
	v_mov_b32_e32 v210, v98
	v_mov_b32_e32 v211, v99
	s_nop 1
	v_permlane16_swap_b32_e32 v208, v210
	v_permlane16_swap_b32_e32 v209, v211
	global_store_dwordx4 v[212:213], v[208:211], off
	s_cbranch_vccnz .LBB0_159
	v_mov_b32_e32 v93, v1
	v_lshl_add_u64 v[98:99], v[128:129], 0, v[92:93]
	v_cvt_pk_fp8_f32 v93, v88, v89
	v_mov_b32_e32 v88, v1
	v_mov_b32_e32 v89, v1
	v_cvt_pk_fp8_f32 v88, v90, v91
	v_cvt_pk_fp8_f32 v89, v84, v85
	v_mov_b32_e32 v90, v1
	v_cvt_pk_fp8_f32 v90, v86, v87
	s_nop 0
	s_nop 0
	s_nop 0
	s_nop 1
	s_nop 0
	s_nop 1
	s_mov_b32 s98, 0x5040100
	s_mov_b32 s100, 0x40000
	s_mov_b32 s101, 0
	v_perm_b32 v214, v88, v93, s98
	v_perm_b32 v215, v90, v89, s98
	v_bfe_i32 v206, v227, 0, 1
	v_and_b32_e32 v206, 0x5050505, v206
	v_xor_b32_e32 v206, 0x6020400, v206
	v_bfe_i32 v207, v227, 1, 1
	v_and_b32_e32 v207, 0x6060606, v207
	v_xor_b32_e32 v207, 0x5040100, v207
	v_mov_b32_dpp v216, v214 quad_perm:[1,0,3,2] row_mask:0xf bank_mask:0xf
	v_mov_b32_dpp v217, v215 quad_perm:[1,0,3,2] row_mask:0xf bank_mask:0xf
	v_and_b32_e32 v220, 3, v227
	v_perm_b32 v214, v216, v214, v206
	v_perm_b32 v215, v217, v215, v206
	v_mul_u32_u24_e32 v220, 0x3fff, v220
	v_mov_b32_e32 v221, 0
	v_mov_b32_dpp v216, v214 quad_perm:[2,3,0,1] row_mask:0xf bank_mask:0xf
	v_mov_b32_dpp v217, v215 quad_perm:[2,3,0,1] row_mask:0xf bank_mask:0xf
	v_lshl_add_u64 v[218:219], v[98:99], 0, v[220:221]
	v_perm_b32 v214, v216, v214, v207
	v_perm_b32 v215, v217, v215, v207
	v_lshl_add_u64 v[220:221], v[218:219], 0, s[100:101]
	global_store_dword v[218:219], v214, off
	global_store_dword v[220:221], v215, off

; DI unsigned pack2(float a, float b) { f2_t v = {a, b}; return __builtin_bit_cast(unsigned, __builtin_convertvector(v, bf2_t)); }
;   DI void operator()(const f32x4 (&acc)[2][2][4][2], const pg8::Unit& u, int wr, int wc, int fr, int fq) const {
;     ...
;           const int row = u.pm * 256 + ai * 128 + wr * 64 + m * 16 + fr;
;           f32x4 x1 = acc[ai][bj][m][0], x2 = acc[ai][bj][m][1];
;           if (mode != 0) {
;             const float pos = (float)(row & (S - 1));
; #pragma unroll
;             for (int e = 0; e < 4; ++e) {
;               const float ang = __fmul_rn(pos, invv[e]);
;               float sn, cs; sincos_big(ang, sn, cs);
;               const float y1 = x1[e] * cs - x2[e] * sn, y2 = x2[e] * cs + x1[e] * sn;
;               x1[e] = y1; x2[e] = y2;
;             }
;           }
;           u16* dp = proj + (size_t)row * NPROJ;
;           *(uint2*)(dp + c1) = make_uint2(pack2(x1[0] * scale, x1[1] * scale), pack2(x1[2] * scale, x1[3] * scale));
;           *(uint2*)(dp + c2) = make_uint2(pack2(x2[0] * scale, x2[1] * scale), pack2(x2[2] * scale, x2[3] * scale));
;           if (gcol0 >= 512 && gcol0 < 768) {
;             const int hd = (gcol0 - 512) >> 6, d0 = (gcol0 & 63) + 4 * fq;
;             unsigned char* vp = vt8 + ((size_t)((row >> 14) * 4 + hd) * 64 + d0) * S + (row & (S - 1));
;             const int w1a = __builtin_amdgcn_cvt_pk_fp8_f32(x1[0], x1[1], 0, false), w1b = __builtin_amdgcn_cvt_pk_fp8_f32(x1[2], x1[3], 0, false);
;             const int w2a = __builtin_amdgcn_cvt_pk_fp8_f32(x2[0], x2[1], 0, false), w2b = __builtin_amdgcn_cvt_pk_fp8_f32(x2[2], x2[3], 0, false);
;             vp[0] = (unsigned char)(w1a & 0xff); vp[(size_t)S] = (unsigned char)((w1a >> 8) & 0xff); vp[(size_t)2 * S] = (unsigned char)(w1b & 0xff); vp[(size_t)3 * S] = (unsigned char)((w1b >> 8) & 0xff);
;             unsigned char* vq = vp + (size_t)16 * S;
;             vq[0] = (unsigned char)(w2a & 0xff); vq[(size_t)S] = (unsigned char)((w2a >> 8) & 0xff); vq[(size_t)2 * S] = (unsigned char)(w2b & 0xff); vq[(size_t)3 * S] = (unsigned char)((w2b >> 8) & 0xff);
.LBB0_171:
	s_and_b32 s6, s19, 0xffffffc0
	s_or_b32 s6, s6, s58
	s_and_b64 s[20:21], s[36:37], exec
	s_cselect_b32 s6, s6, s19
	s_cselect_b32 s20, 32, 16
	v_or_b32_e32 v88, s6, v180
	s_addk_i32 s19, 0xfe00
	v_ashrrev_i32_e32 v89, 31, v88
	s_lshr_b32 s6, s19, 6
	v_pk_mul_f32 v[90:91], v[84:85], v[80:81] op_sel_hi:[0,1]
	v_pk_mul_f32 v[106:107], v[84:85], v[82:83] op_sel_hi:[0,1]
	v_or_b32_e32 v86, s20, v88
	s_or_b32 s20, s7, s6
	v_cvt_pk_bf16_f32 v90, v90, v91
	v_cvt_pk_bf16_f32 v91, v106, v107
	v_lshl_add_u64 v[106:107], v[88:89], 1, v[168:169]
	v_ashrrev_i32_e32 v87, 31, v86
	s_ashr_i32 s21, s20, 31
	v_bfe_u32 v222, v227, 4, 1
	v_mul_u32_u24_e32 v222, 0x17ff8, v222
	v_mov_b32_e32 v223, 0
	v_mov_b32_e32 v200, v90
	v_mov_b32_e32 v201, v91
	v_lshl_add_u64 v[204:205], v[106:107], 0, v[222:223]
	v_pk_mul_f32 v[90:91], v[84:85], v[76:77] op_sel_hi:[0,1]
	v_pk_mul_f32 v[106:107], v[84:85], v[78:79] op_sel_hi:[0,1]
	s_lshl_b64 s[20:21], s[20:21], 20
	v_cvt_pk_bf16_f32 v90, v90, v91
	v_cvt_pk_bf16_f32 v91, v106, v107
	v_lshl_add_u64 v[106:107], v[86:87], 1, v[168:169]
	v_mov_b32_e32 v208, v90
	v_mov_b32_e32 v209, v91
	v_lshl_add_u64 v[212:213], v[106:107], 0, v[222:223]
	s_and_b64 vcc, exec, s[40:41]
	v_lshl_add_u64 v[90:91], v[162:163], 0, s[20:21]
	s_cbranch_vccnz .LBB0_173
	v_lshl_add_u64 v[106:107], v[90:91], 0, v[0:1]
	v_mov_b32_e32 v0, v1
	v_cvt_pk_fp8_f32 v0, v80, v81
	v_mov_b32_e32 v80, v1
	v_mov_b32_e32 v81, v1
	v_cvt_pk_fp8_f32 v80, v82, v83
	v_cvt_pk_fp8_f32 v81, v76, v77
	s_nop 0
	v_mov_b32_e32 v82, v1
	s_nop 0
	v_cvt_pk_fp8_f32 v82, v78, v79
	s_nop 0
	s_nop 0
	s_nop 0
	s_nop 1
	s_mov_b32 s98, 0x5040100
	s_mov_b32 s100, 0x40000
	s_mov_b32 s101, 0
	v_perm_b32 v214, v80, v0, s98
	v_perm_b32 v215, v82, v81, s98
	v_bfe_i32 v206, v227, 0, 1
	v_and_b32_e32 v206, 0x5050505, v206
	v_xor_b32_e32 v206, 0x6020400, v206
	v_bfe_i32 v207, v227, 1, 1
	v_and_b32_e32 v207, 0x6060606, v207
	v_xor_b32_e32 v207, 0x5040100, v207
	v_mov_b32_dpp v216, v214 quad_perm:[1,0,3,2] row_mask:0xf bank_mask:0xf
	v_mov_b32_dpp v217, v215 quad_perm:[1,0,3,2] row_mask:0xf bank_mask:0xf
	v_and_b32_e32 v220, 3, v227
	v_perm_b32 v214, v216, v214, v206
	v_perm_b32 v215, v217, v215, v206
	v_mul_u32_u24_e32 v220, 0x3fff, v220
	v_mov_b32_e32 v221, 0
	v_mov_b32_dpp v216, v214 quad_perm:[2,3,0,1] row_mask:0xf bank_mask:0xf
	v_mov_b32_dpp v217, v215 quad_perm:[2,3,0,1] row_mask:0xf bank_mask:0xf
	v_lshl_add_u64 v[218:219], v[106:107], 0, v[220:221]
	v_perm_b32 v214, v216, v214, v207
	v_perm_b32 v215, v217, v215, v207
	v_lshl_add_u64 v[220:221], v[218:219], 0, s[100:101]
	global_store_dword v[218:219], v214, off
	global_store_dword v[220:221], v215, off

; DI unsigned pack2(float a, float b) { f2_t v = {a, b}; return __builtin_bit_cast(unsigned, __builtin_convertvector(v, bf2_t)); }
;   DI void operator()(const f32x4 (&acc)[2][2][4][2], const pg8::Unit& u, int wr, int wc, int fr, int fq) const {
;     ...
;           u16* dp = proj + (size_t)row * NPROJ;
;           *(uint2*)(dp + c1) = make_uint2(pack2(x1[0] * scale, x1[1] * scale), pack2(x1[2] * scale, x1[3] * scale));
;           *(uint2*)(dp + c2) = make_uint2(pack2(x2[0] * scale, x2[1] * scale), pack2(x2[2] * scale, x2[3] * scale));
;           if (gcol0 >= 512 && gcol0 < 768) {
;             const int hd = (gcol0 - 512) >> 6, d0 = (gcol0 & 63) + 4 * fq;
;             unsigned char* vp = vt8 + ((size_t)((row >> 14) * 4 + hd) * 64 + d0) * S + (row & (S - 1));
;             const int w1a = __builtin_amdgcn_cvt_pk_fp8_f32(x1[0], x1[1], 0, false), w1b = __builtin_amdgcn_cvt_pk_fp8_f32(x1[2], x1[3], 0, false);
;             const int w2a = __builtin_amdgcn_cvt_pk_fp8_f32(x2[0], x2[1], 0, false), w2b = __builtin_amdgcn_cvt_pk_fp8_f32(x2[2], x2[3], 0, false);
;             vp[0] = (unsigned char)(w1a & 0xff); vp[(size_t)S] = (unsigned char)((w1a >> 8) & 0xff); vp[(size_t)2 * S] = (unsigned char)(w1b & 0xff); vp[(size_t)3 * S] = (unsigned char)((w1b >> 8) & 0xff);
;             unsigned char* vq = vp + (size_t)16 * S;
;             vq[0] = (unsigned char)(w2a & 0xff); vq[(size_t)S] = (unsigned char)((w2a >> 8) & 0xff); vq[(size_t)2 * S] = (unsigned char)(w2b & 0xff); vq[(size_t)3 * S] = (unsigned char)((w2b >> 8) & 0xff);
.LBB0_175:
	v_mov_b32_e32 v85, v84
	v_pk_mul_f32 v[76:77], v[84:85], v[72:73]
	v_pk_mul_f32 v[78:79], v[84:85], v[74:75]
	v_cvt_pk_bf16_f32 v76, v76, v77
	v_cvt_pk_bf16_f32 v77, v78, v79
	v_lshl_add_u64 v[78:79], v[88:89], 1, v[150:151]
	v_mov_b32_e32 v202, v76
	v_mov_b32_e32 v203, v77
	s_nop 1
	v_permlane16_swap_b32_e32 v200, v202
	v_permlane16_swap_b32_e32 v201, v203
	global_store_dwordx4 v[204:205], v[200:203], off
	v_pk_mul_f32 v[76:77], v[84:85], v[68:69]
	v_pk_mul_f32 v[78:79], v[84:85], v[70:71]
	v_cvt_pk_bf16_f32 v76, v76, v77
	v_cvt_pk_bf16_f32 v77, v78, v79
	v_lshl_add_u64 v[78:79], v[86:87], 1, v[150:151]
	s_and_b64 vcc, exec, s[40:41]
	v_mov_b32_e32 v210, v76
	v_mov_b32_e32 v211, v77
	s_nop 1
	v_permlane16_swap_b32_e32 v208, v210
	v_permlane16_swap_b32_e32 v209, v211
	global_store_dwordx4 v[212:213], v[208:211], off
	s_cbranch_vccnz .LBB0_177
	v_mov_b32_e32 v0, v1
	v_cvt_pk_fp8_f32 v0, v72, v73
	v_mov_b32_e32 v149, v1
	v_lshl_add_u64 v[76:77], v[90:91], 0, v[148:149]
	v_mov_b32_e32 v72, v1
	v_mov_b32_e32 v73, v1
	v_cvt_pk_fp8_f32 v72, v74, v75
	v_cvt_pk_fp8_f32 v73, v68, v69
	s_nop 0
	v_mov_b32_e32 v74, v1
	s_nop 0
	v_cvt_pk_fp8_f32 v74, v70, v71
	s_nop 0
	s_nop 0
	s_nop 0
	s_nop 1
	s_mov_b32 s98, 0x5040100
	s_mov_b32 s100, 0x40000
	s_mov_b32 s101, 0
	v_perm_b32 v214, v72, v0, s98
	v_perm_b32 v215, v74, v73, s98
	v_bfe_i32 v206, v227, 0, 1
	v_and_b32_e32 v206, 0x5050505, v206
	v_xor_b32_e32 v206, 0x6020400, v206
	v_bfe_i32 v207, v227, 1, 1
	v_and_b32_e32 v207, 0x6060606, v207
	v_xor_b32_e32 v207, 0x5040100, v207
	v_mov_b32_dpp v216, v214 quad_perm:[1,0,3,2] row_mask:0xf bank_mask:0xf
	v_mov_b32_dpp v217, v215 quad_perm:[1,0,3,2] row_mask:0xf bank_mask:0xf
	v_and_b32_e32 v220, 3, v227
	v_perm_b32 v214, v216, v214, v206
	v_perm_b32 v215, v217, v215, v206
	v_mul_u32_u24_e32 v220, 0x3fff, v220
	v_mov_b32_e32 v221, 0
	v_mov_b32_dpp v216, v214 quad_perm:[2,3,0,1] row_mask:0xf bank_mask:0xf
	v_mov_b32_dpp v217, v215 quad_perm:[2,3,0,1] row_mask:0xf bank_mask:0xf
	v_lshl_add_u64 v[218:219], v[76:77], 0, v[220:221]
	v_perm_b32 v214, v216, v214, v207
	v_perm_b32 v215, v217, v215, v207
	v_lshl_add_u64 v[220:221], v[218:219], 0, s[100:101]
	global_store_dword v[218:219], v214, off
	global_store_dword v[220:221], v215, off

; DI unsigned pack2(float a, float b) { f2_t v = {a, b}; return __builtin_bit_cast(unsigned, __builtin_convertvector(v, bf2_t)); }
;   DI void operator()(const f32x4 (&acc)[2][2][4][2], const pg8::Unit& u, int wr, int wc, int fr, int fq) const {
;     ...
;           u16* dp = proj + (size_t)row * NPROJ;
;           *(uint2*)(dp + c1) = make_uint2(pack2(x1[0] * scale, x1[1] * scale), pack2(x1[2] * scale, x1[3] * scale));
;           *(uint2*)(dp + c2) = make_uint2(pack2(x2[0] * scale, x2[1] * scale), pack2(x2[2] * scale, x2[3] * scale));
;           if (gcol0 >= 512 && gcol0 < 768) {
;             const int hd = (gcol0 - 512) >> 6, d0 = (gcol0 & 63) + 4 * fq;
;             unsigned char* vp = vt8 + ((size_t)((row >> 14) * 4 + hd) * 64 + d0) * S + (row & (S - 1));
;             const int w1a = __builtin_amdgcn_cvt_pk_fp8_f32(x1[0], x1[1], 0, false), w1b = __builtin_amdgcn_cvt_pk_fp8_f32(x1[2], x1[3], 0, false);
;             const int w2a = __builtin_amdgcn_cvt_pk_fp8_f32(x2[0], x2[1], 0, false), w2b = __builtin_amdgcn_cvt_pk_fp8_f32(x2[2], x2[3], 0, false);
;             vp[0] = (unsigned char)(w1a & 0xff); vp[(size_t)S] = (unsigned char)((w1a >> 8) & 0xff); vp[(size_t)2 * S] = (unsigned char)(w1b & 0xff); vp[(size_t)3 * S] = (unsigned char)((w1b >> 8) & 0xff);
;             unsigned char* vq = vp + (size_t)16 * S;
;             vq[0] = (unsigned char)(w2a & 0xff); vq[(size_t)S] = (unsigned char)((w2a >> 8) & 0xff); vq[(size_t)2 * S] = (unsigned char)(w2b & 0xff); vq[(size_t)3 * S] = (unsigned char)((w2b >> 8) & 0xff);
.LBB0_179:
	v_pk_mul_f32 v[68:69], v[84:85], v[64:65]
	v_pk_mul_f32 v[70:71], v[84:85], v[66:67]
	v_cvt_pk_bf16_f32 v68, v68, v69
	v_cvt_pk_bf16_f32 v69, v70, v71
	v_lshl_add_u64 v[70:71], v[88:89], 1, v[142:143]
	v_bfe_u32 v222, v227, 4, 1
	v_mul_u32_u24_e32 v222, 0x17ff8, v222
	v_mov_b32_e32 v223, 0
	v_mov_b32_e32 v200, v68
	v_mov_b32_e32 v201, v69
	v_lshl_add_u64 v[204:205], v[70:71], 0, v[222:223]
	v_pk_mul_f32 v[68:69], v[84:85], v[60:61]
	v_pk_mul_f32 v[70:71], v[84:85], v[62:63]
	v_cvt_pk_bf16_f32 v68, v68, v69
	v_cvt_pk_bf16_f32 v69, v70, v71
	v_lshl_add_u64 v[70:71], v[86:87], 1, v[142:143]
	s_and_b64 vcc, exec, s[40:41]
	v_mov_b32_e32 v208, v68
	v_mov_b32_e32 v209, v69
	v_lshl_add_u64 v[212:213], v[70:71], 0, v[222:223]
	s_cbranch_vccnz .LBB0_181
	v_mov_b32_e32 v0, v1
	v_cvt_pk_fp8_f32 v0, v64, v65
	v_mov_b32_e32 v141, v1
	v_lshl_add_u64 v[68:69], v[90:91], 0, v[140:141]
	v_mov_b32_e32 v64, v1
	v_mov_b32_e32 v65, v1
	v_cvt_pk_fp8_f32 v64, v66, v67
	v_cvt_pk_fp8_f32 v65, v60, v61
	s_nop 0
	v_mov_b32_e32 v66, v1
	s_nop 0
	v_cvt_pk_fp8_f32 v66, v62, v63
	s_nop 0
	s_nop 0
	s_nop 0
	s_nop 1
	s_mov_b32 s98, 0x5040100
	s_mov_b32 s100, 0x40000
	s_mov_b32 s101, 0
	v_perm_b32 v214, v64, v0, s98
	v_perm_b32 v215, v66, v65, s98
	v_bfe_i32 v206, v227, 0, 1
	v_and_b32_e32 v206, 0x5050505, v206
	v_xor_b32_e32 v206, 0x6020400, v206
	v_bfe_i32 v207, v227, 1, 1
	v_and_b32_e32 v207, 0x6060606, v207
	v_xor_b32_e32 v207, 0x5040100, v207
	v_mov_b32_dpp v216, v214 quad_perm:[1,0,3,2] row_mask:0xf bank_mask:0xf
	v_mov_b32_dpp v217, v215 quad_perm:[1,0,3,2] row_mask:0xf bank_mask:0xf
	v_and_b32_e32 v220, 3, v227
	v_perm_b32 v214, v216, v214, v206
	v_perm_b32 v215, v217, v215, v206
	v_mul_u32_u24_e32 v220, 0x3fff, v220
	v_mov_b32_e32 v221, 0
	v_mov_b32_dpp v216, v214 quad_perm:[2,3,0,1] row_mask:0xf bank_mask:0xf
	v_mov_b32_dpp v217, v215 quad_perm:[2,3,0,1] row_mask:0xf bank_mask:0xf
	v_lshl_add_u64 v[218:219], v[68:69], 0, v[220:221]
	v_perm_b32 v214, v216, v214, v207
	v_perm_b32 v215, v217, v215, v207
	v_lshl_add_u64 v[220:221], v[218:219], 0, s[100:101]
	global_store_dword v[218:219], v214, off
	global_store_dword v[220:221], v215, off

; DI unsigned pack2(float a, float b) { f2_t v = {a, b}; return __builtin_bit_cast(unsigned, __builtin_convertvector(v, bf2_t)); }
;   DI void operator()(const f32x4 (&acc)[2][2][4][2], const pg8::Unit& u, int wr, int wc, int fr, int fq) const {
;     ...
;           u16* dp = proj + (size_t)row * NPROJ;
;           *(uint2*)(dp + c1) = make_uint2(pack2(x1[0] * scale, x1[1] * scale), pack2(x1[2] * scale, x1[3] * scale));
;           *(uint2*)(dp + c2) = make_uint2(pack2(x2[0] * scale, x2[1] * scale), pack2(x2[2] * scale, x2[3] * scale));
;           if (gcol0 >= 512 && gcol0 < 768) {
;             const int hd = (gcol0 - 512) >> 6, d0 = (gcol0 & 63) + 4 * fq;
;             unsigned char* vp = vt8 + ((size_t)((row >> 14) * 4 + hd) * 64 + d0) * S + (row & (S - 1));
;             const int w1a = __builtin_amdgcn_cvt_pk_fp8_f32(x1[0], x1[1], 0, false), w1b = __builtin_amdgcn_cvt_pk_fp8_f32(x1[2], x1[3], 0, false);
;             const int w2a = __builtin_amdgcn_cvt_pk_fp8_f32(x2[0], x2[1], 0, false), w2b = __builtin_amdgcn_cvt_pk_fp8_f32(x2[2], x2[3], 0, false);
;             vp[0] = (unsigned char)(w1a & 0xff); vp[(size_t)S] = (unsigned char)((w1a >> 8) & 0xff); vp[(size_t)2 * S] = (unsigned char)(w1b & 0xff); vp[(size_t)3 * S] = (unsigned char)((w1b >> 8) & 0xff);
;             unsigned char* vq = vp + (size_t)16 * S;
;             vq[0] = (unsigned char)(w2a & 0xff); vq[(size_t)S] = (unsigned char)((w2a >> 8) & 0xff); vq[(size_t)2 * S] = (unsigned char)(w2b & 0xff); vq[(size_t)3 * S] = (unsigned char)((w2b >> 8) & 0xff);
.LBB0_183:
	v_pk_mul_f32 v[60:61], v[84:85], v[56:57]
	v_pk_mul_f32 v[62:63], v[84:85], v[58:59]
	v_cvt_pk_bf16_f32 v60, v60, v61
	v_cvt_pk_bf16_f32 v61, v62, v63
	v_lshl_add_u64 v[62:63], v[88:89], 1, v[134:135]
	v_mov_b32_e32 v202, v60
	v_mov_b32_e32 v203, v61
	s_nop 1
	v_permlane16_swap_b32_e32 v200, v202
	v_permlane16_swap_b32_e32 v201, v203
	global_store_dwordx4 v[204:205], v[200:203], off
	v_pk_mul_f32 v[60:61], v[84:85], v[52:53]
	v_pk_mul_f32 v[62:63], v[84:85], v[54:55]
	v_cvt_pk_bf16_f32 v60, v60, v61
	v_cvt_pk_bf16_f32 v61, v62, v63
	v_lshl_add_u64 v[62:63], v[86:87], 1, v[134:135]
	s_and_b64 vcc, exec, s[40:41]
	v_mov_b32_e32 v210, v60
	v_mov_b32_e32 v211, v61
	s_nop 1
	v_permlane16_swap_b32_e32 v208, v210
	v_permlane16_swap_b32_e32 v209, v211
	global_store_dwordx4 v[212:213], v[208:211], off
	s_cbranch_vccnz .LBB0_185
	v_mov_b32_e32 v0, v1
	v_cvt_pk_fp8_f32 v0, v56, v57
	v_mov_b32_e32 v133, v1
	v_lshl_add_u64 v[60:61], v[90:91], 0, v[132:133]
	v_mov_b32_e32 v56, v1
	v_mov_b32_e32 v57, v1
	v_cvt_pk_fp8_f32 v56, v58, v59
	v_cvt_pk_fp8_f32 v57, v52, v53
	s_nop 0
	v_mov_b32_e32 v58, v1
	s_nop 0
	v_cvt_pk_fp8_f32 v58, v54, v55
	s_nop 0
	s_nop 0
	s_nop 0
	s_nop 1
	s_mov_b32 s98, 0x5040100
	s_mov_b32 s100, 0x40000
	s_mov_b32 s101, 0
	v_perm_b32 v214, v56, v0, s98
	v_perm_b32 v215, v58, v57, s98
	v_bfe_i32 v206, v227, 0, 1
	v_and_b32_e32 v206, 0x5050505, v206
	v_xor_b32_e32 v206, 0x6020400, v206
	v_bfe_i32 v207, v227, 1, 1
	v_and_b32_e32 v207, 0x6060606, v207
	v_xor_b32_e32 v207, 0x5040100, v207
	v_mov_b32_dpp v216, v214 quad_perm:[1,0,3,2] row_mask:0xf bank_mask:0xf
	v_mov_b32_dpp v217, v215 quad_perm:[1,0,3,2] row_mask:0xf bank_mask:0xf
	v_and_b32_e32 v220, 3, v227
	v_perm_b32 v214, v216, v214, v206
	v_perm_b32 v215, v217, v215, v206
	v_mul_u32_u24_e32 v220, 0x3fff, v220
	v_mov_b32_e32 v221, 0
	v_mov_b32_dpp v216, v214 quad_perm:[2,3,0,1] row_mask:0xf bank_mask:0xf
	v_mov_b32_dpp v217, v215 quad_perm:[2,3,0,1] row_mask:0xf bank_mask:0xf
	v_lshl_add_u64 v[218:219], v[60:61], 0, v[220:221]
	v_perm_b32 v214, v216, v214, v207
	v_perm_b32 v215, v217, v215, v207
	v_lshl_add_u64 v[220:221], v[218:219], 0, s[100:101]
	global_store_dword v[218:219], v214, off
	global_store_dword v[220:221], v215, off

; DI unsigned pack2(float a, float b) { f2_t v = {a, b}; return __builtin_bit_cast(unsigned, __builtin_convertvector(v, bf2_t)); }
;   DI void operator()(const f32x4 (&acc)[2][2][4][2], const pg8::Unit& u, int wr, int wc, int fr, int fq) const {
;     ...
;           const int row = u.pm * 256 + ai * 128 + wr * 64 + m * 16 + fr;
;           f32x4 x1 = acc[ai][bj][m][0], x2 = acc[ai][bj][m][1];
;           if (mode != 0) {
;             const float pos = (float)(row & (S - 1));
; #pragma unroll
;             for (int e = 0; e < 4; ++e) {
;               const float ang = __fmul_rn(pos, invv[e]);
;               float sn, cs; sincos_big(ang, sn, cs);
;               const float y1 = x1[e] * cs - x2[e] * sn, y2 = x2[e] * cs + x1[e] * sn;
;               x1[e] = y1; x2[e] = y2;
;             }
;           }
;           u16* dp = proj + (size_t)row * NPROJ;
;           *(uint2*)(dp + c1) = make_uint2(pack2(x1[0] * scale, x1[1] * scale), pack2(x1[2] * scale, x1[3] * scale));
;           *(uint2*)(dp + c2) = make_uint2(pack2(x2[0] * scale, x2[1] * scale), pack2(x2[2] * scale, x2[3] * scale));
;           if (gcol0 >= 512 && gcol0 < 768) {
;             const int hd = (gcol0 - 512) >> 6, d0 = (gcol0 & 63) + 4 * fq;
;             unsigned char* vp = vt8 + ((size_t)((row >> 14) * 4 + hd) * 64 + d0) * S + (row & (S - 1));
;             const int w1a = __builtin_amdgcn_cvt_pk_fp8_f32(x1[0], x1[1], 0, false), w1b = __builtin_amdgcn_cvt_pk_fp8_f32(x1[2], x1[3], 0, false);
;             const int w2a = __builtin_amdgcn_cvt_pk_fp8_f32(x2[0], x2[1], 0, false), w2b = __builtin_amdgcn_cvt_pk_fp8_f32(x2[2], x2[3], 0, false);
;             vp[0] = (unsigned char)(w1a & 0xff); vp[(size_t)S] = (unsigned char)((w1a >> 8) & 0xff); vp[(size_t)2 * S] = (unsigned char)(w1b & 0xff); vp[(size_t)3 * S] = (unsigned char)((w1b >> 8) & 0xff);
;             unsigned char* vq = vp + (size_t)16 * S;
;             vq[0] = (unsigned char)(w2a & 0xff); vq[(size_t)S] = (unsigned char)((w2a >> 8) & 0xff); vq[(size_t)2 * S] = (unsigned char)(w2b & 0xff); vq[(size_t)3 * S] = (unsigned char)((w2b >> 8) & 0xff);
.LBB0_187:
	v_pk_mul_f32 v[52:53], v[84:85], v[48:49]
	v_pk_mul_f32 v[54:55], v[84:85], v[50:51]
	s_or_b32 s6, s18, s6
	v_cvt_pk_bf16_f32 v52, v52, v53
	v_cvt_pk_bf16_f32 v53, v54, v55
	v_lshl_add_u64 v[54:55], v[88:89], 1, v[126:127]
	s_ashr_i32 s7, s6, 31
	v_bfe_u32 v222, v227, 4, 1
	v_mul_u32_u24_e32 v222, 0x17ff8, v222
	v_mov_b32_e32 v223, 0
	v_mov_b32_e32 v200, v52
	v_mov_b32_e32 v201, v53
	v_lshl_add_u64 v[204:205], v[54:55], 0, v[222:223]
	v_pk_mul_f32 v[52:53], v[84:85], v[44:45]
	v_pk_mul_f32 v[54:55], v[84:85], v[46:47]
	s_lshl_b64 s[6:7], s[6:7], 20
	v_cvt_pk_bf16_f32 v52, v52, v53
	v_cvt_pk_bf16_f32 v53, v54, v55
	v_lshl_add_u64 v[54:55], v[86:87], 1, v[126:127]
	v_mov_b32_e32 v208, v52
	v_mov_b32_e32 v209, v53
	v_lshl_add_u64 v[212:213], v[54:55], 0, v[222:223]
	s_and_b64 vcc, exec, s[40:41]
	v_lshl_add_u64 v[52:53], v[162:163], 0, s[6:7]
	s_cbranch_vccnz .LBB0_189
	v_mov_b32_e32 v0, v1
	v_cvt_pk_fp8_f32 v0, v48, v49
	v_mov_b32_e32 v125, v1
	v_lshl_add_u64 v[54:55], v[52:53], 0, v[124:125]
	v_mov_b32_e32 v48, v1
	v_mov_b32_e32 v49, v1
	v_cvt_pk_fp8_f32 v48, v50, v51
	v_cvt_pk_fp8_f32 v49, v44, v45
	s_nop 0
	v_mov_b32_e32 v50, v1
	s_nop 0
	v_cvt_pk_fp8_f32 v50, v46, v47
	s_nop 0
	s_nop 0
	s_nop 0
	s_nop 1
	s_mov_b32 s98, 0x5040100
	s_mov_b32 s100, 0x40000
	s_mov_b32 s101, 0
	v_perm_b32 v214, v48, v0, s98
	v_perm_b32 v215, v50, v49, s98
	v_bfe_i32 v206, v227, 0, 1
	v_and_b32_e32 v206, 0x5050505, v206
	v_xor_b32_e32 v206, 0x6020400, v206
	v_bfe_i32 v207, v227, 1, 1
	v_and_b32_e32 v207, 0x6060606, v207
	v_xor_b32_e32 v207, 0x5040100, v207
	v_mov_b32_dpp v216, v214 quad_perm:[1,0,3,2] row_mask:0xf bank_mask:0xf
	v_mov_b32_dpp v217, v215 quad_perm:[1,0,3,2] row_mask:0xf bank_mask:0xf
	v_and_b32_e32 v220, 3, v227
	v_perm_b32 v214, v216, v214, v206
	v_perm_b32 v215, v217, v215, v206
	v_mul_u32_u24_e32 v220, 0x3fff, v220
	v_mov_b32_e32 v221, 0
	v_mov_b32_dpp v216, v214 quad_perm:[2,3,0,1] row_mask:0xf bank_mask:0xf
	v_mov_b32_dpp v217, v215 quad_perm:[2,3,0,1] row_mask:0xf bank_mask:0xf
	v_lshl_add_u64 v[218:219], v[54:55], 0, v[220:221]
	v_perm_b32 v214, v216, v214, v207
	v_perm_b32 v215, v217, v215, v207
	v_lshl_add_u64 v[220:221], v[218:219], 0, s[100:101]
	global_store_dword v[218:219], v214, off
	global_store_dword v[220:221], v215, off

; DI unsigned pack2(float a, float b) { f2_t v = {a, b}; return __builtin_bit_cast(unsigned, __builtin_convertvector(v, bf2_t)); }
;   DI void operator()(const f32x4 (&acc)[2][2][4][2], const pg8::Unit& u, int wr, int wc, int fr, int fq) const {
;     ...
;           u16* dp = proj + (size_t)row * NPROJ;
;           *(uint2*)(dp + c1) = make_uint2(pack2(x1[0] * scale, x1[1] * scale), pack2(x1[2] * scale, x1[3] * scale));
;           *(uint2*)(dp + c2) = make_uint2(pack2(x2[0] * scale, x2[1] * scale), pack2(x2[2] * scale, x2[3] * scale));
;           if (gcol0 >= 512 && gcol0 < 768) {
;             const int hd = (gcol0 - 512) >> 6, d0 = (gcol0 & 63) + 4 * fq;
;             unsigned char* vp = vt8 + ((size_t)((row >> 14) * 4 + hd) * 64 + d0) * S + (row & (S - 1));
;             const int w1a = __builtin_amdgcn_cvt_pk_fp8_f32(x1[0], x1[1], 0, false), w1b = __builtin_amdgcn_cvt_pk_fp8_f32(x1[2], x1[3], 0, false);
;             const int w2a = __builtin_amdgcn_cvt_pk_fp8_f32(x2[0], x2[1], 0, false), w2b = __builtin_amdgcn_cvt_pk_fp8_f32(x2[2], x2[3], 0, false);
;             vp[0] = (unsigned char)(w1a & 0xff); vp[(size_t)S] = (unsigned char)((w1a >> 8) & 0xff); vp[(size_t)2 * S] = (unsigned char)(w1b & 0xff); vp[(size_t)3 * S] = (unsigned char)((w1b >> 8) & 0xff);
;             unsigned char* vq = vp + (size_t)16 * S;
;             vq[0] = (unsigned char)(w2a & 0xff); vq[(size_t)S] = (unsigned char)((w2a >> 8) & 0xff); vq[(size_t)2 * S] = (unsigned char)(w2b & 0xff); vq[(size_t)3 * S] = (unsigned char)((w2b >> 8) & 0xff);
.LBB0_191:
	v_pk_mul_f32 v[44:45], v[84:85], v[40:41]
	v_pk_mul_f32 v[46:47], v[84:85], v[42:43]
	v_cvt_pk_bf16_f32 v44, v44, v45
	v_cvt_pk_bf16_f32 v45, v46, v47
	v_lshl_add_u64 v[46:47], v[88:89], 1, v[118:119]
	v_mov_b32_e32 v202, v44
	v_mov_b32_e32 v203, v45
	s_nop 1
	v_permlane16_swap_b32_e32 v200, v202
	v_permlane16_swap_b32_e32 v201, v203
	global_store_dwordx4 v[204:205], v[200:203], off
	v_pk_mul_f32 v[44:45], v[84:85], v[36:37]
	v_pk_mul_f32 v[46:47], v[84:85], v[38:39]
	v_cvt_pk_bf16_f32 v44, v44, v45
	v_cvt_pk_bf16_f32 v45, v46, v47
	v_lshl_add_u64 v[46:47], v[86:87], 1, v[118:119]
	s_and_b64 vcc, exec, s[40:41]
	v_mov_b32_e32 v210, v44
	v_mov_b32_e32 v211, v45
	s_nop 1
	v_permlane16_swap_b32_e32 v208, v210
	v_permlane16_swap_b32_e32 v209, v211
	global_store_dwordx4 v[212:213], v[208:211], off
	s_cbranch_vccnz .LBB0_193
	v_mov_b32_e32 v0, v1
	v_cvt_pk_fp8_f32 v0, v40, v41
	v_mov_b32_e32 v117, v1
	v_lshl_add_u64 v[44:45], v[52:53], 0, v[116:117]
	v_mov_b32_e32 v40, v1
	v_mov_b32_e32 v41, v1
	v_cvt_pk_fp8_f32 v40, v42, v43
	v_cvt_pk_fp8_f32 v41, v36, v37
	s_nop 0
	v_mov_b32_e32 v42, v1
	s_nop 0
	v_cvt_pk_fp8_f32 v42, v38, v39
	s_nop 0
	s_nop 0
	s_nop 0
	s_nop 1
	s_mov_b32 s98, 0x5040100
	s_mov_b32 s100, 0x40000
	s_mov_b32 s101, 0
	v_perm_b32 v214, v40, v0, s98
	v_perm_b32 v215, v42, v41, s98
	v_bfe_i32 v206, v227, 0, 1
	v_and_b32_e32 v206, 0x5050505, v206
	v_xor_b32_e32 v206, 0x6020400, v206
	v_bfe_i32 v207, v227, 1, 1
	v_and_b32_e32 v207, 0x6060606, v207
	v_xor_b32_e32 v207, 0x5040100, v207
	v_mov_b32_dpp v216, v214 quad_perm:[1,0,3,2] row_mask:0xf bank_mask:0xf
	v_mov_b32_dpp v217, v215 quad_perm:[1,0,3,2] row_mask:0xf bank_mask:0xf
	v_and_b32_e32 v220, 3, v227
	v_perm_b32 v214, v216, v214, v206
	v_perm_b32 v215, v217, v215, v206
	v_mul_u32_u24_e32 v220, 0x3fff, v220
	v_mov_b32_e32 v221, 0
	v_mov_b32_dpp v216, v214 quad_perm:[2,3,0,1] row_mask:0xf bank_mask:0xf
	v_mov_b32_dpp v217, v215 quad_perm:[2,3,0,1] row_mask:0xf bank_mask:0xf
	v_lshl_add_u64 v[218:219], v[44:45], 0, v[220:221]
	v_perm_b32 v214, v216, v214, v207
	v_perm_b32 v215, v217, v215, v207
	v_lshl_add_u64 v[220:221], v[218:219], 0, s[100:101]
	global_store_dword v[218:219], v214, off
	global_store_dword v[220:221], v215, off

; DI unsigned pack2(float a, float b) { f2_t v = {a, b}; return __builtin_bit_cast(unsigned, __builtin_convertvector(v, bf2_t)); }
;   DI void operator()(const f32x4 (&acc)[2][2][4][2], const pg8::Unit& u, int wr, int wc, int fr, int fq) const {
;     ...
;           u16* dp = proj + (size_t)row * NPROJ;
;           *(uint2*)(dp + c1) = make_uint2(pack2(x1[0] * scale, x1[1] * scale), pack2(x1[2] * scale, x1[3] * scale));
;           *(uint2*)(dp + c2) = make_uint2(pack2(x2[0] * scale, x2[1] * scale), pack2(x2[2] * scale, x2[3] * scale));
;           if (gcol0 >= 512 && gcol0 < 768) {
;             const int hd = (gcol0 - 512) >> 6, d0 = (gcol0 & 63) + 4 * fq;
;             unsigned char* vp = vt8 + ((size_t)((row >> 14) * 4 + hd) * 64 + d0) * S + (row & (S - 1));
;             const int w1a = __builtin_amdgcn_cvt_pk_fp8_f32(x1[0], x1[1], 0, false), w1b = __builtin_amdgcn_cvt_pk_fp8_f32(x1[2], x1[3], 0, false);
;             const int w2a = __builtin_amdgcn_cvt_pk_fp8_f32(x2[0], x2[1], 0, false), w2b = __builtin_amdgcn_cvt_pk_fp8_f32(x2[2], x2[3], 0, false);
;             vp[0] = (unsigned char)(w1a & 0xff); vp[(size_t)S] = (unsigned char)((w1a >> 8) & 0xff); vp[(size_t)2 * S] = (unsigned char)(w1b & 0xff); vp[(size_t)3 * S] = (unsigned char)((w1b >> 8) & 0xff);
;             unsigned char* vq = vp + (size_t)16 * S;
;             vq[0] = (unsigned char)(w2a & 0xff); vq[(size_t)S] = (unsigned char)((w2a >> 8) & 0xff); vq[(size_t)2 * S] = (unsigned char)(w2b & 0xff); vq[(size_t)3 * S] = (unsigned char)((w2b >> 8) & 0xff);
.LBB0_195:
	v_pk_mul_f32 v[36:37], v[84:85], v[32:33]
	v_pk_mul_f32 v[38:39], v[84:85], v[34:35]
	v_cvt_pk_bf16_f32 v36, v36, v37
	v_cvt_pk_bf16_f32 v37, v38, v39
	v_lshl_add_u64 v[38:39], v[88:89], 1, v[102:103]
	v_bfe_u32 v222, v227, 4, 1
	v_mul_u32_u24_e32 v222, 0x17ff8, v222
	v_mov_b32_e32 v223, 0
	v_mov_b32_e32 v200, v36
	v_mov_b32_e32 v201, v37
	v_lshl_add_u64 v[204:205], v[38:39], 0, v[222:223]
	v_pk_mul_f32 v[36:37], v[84:85], v[10:11]
	v_pk_mul_f32 v[38:39], v[84:85], v[12:13]
	v_cvt_pk_bf16_f32 v36, v36, v37
	v_cvt_pk_bf16_f32 v37, v38, v39
	v_lshl_add_u64 v[38:39], v[86:87], 1, v[102:103]
	s_and_b64 vcc, exec, s[40:41]
	v_mov_b32_e32 v208, v36
	v_mov_b32_e32 v209, v37
	v_lshl_add_u64 v[212:213], v[38:39], 0, v[222:223]
	s_cbranch_vccnz .LBB0_197
	v_mov_b32_e32 v0, v1
	v_cvt_pk_fp8_f32 v0, v32, v33
	v_mov_b32_e32 v101, v1
	v_lshl_add_u64 v[36:37], v[52:53], 0, v[100:101]
	v_mov_b32_e32 v32, v1
	v_mov_b32_e32 v33, v1
	v_cvt_pk_fp8_f32 v32, v34, v35
	v_cvt_pk_fp8_f32 v33, v10, v11
	s_nop 0
	v_mov_b32_e32 v34, v1
	s_nop 0
	v_cvt_pk_fp8_f32 v34, v12, v13
	s_nop 0
	s_nop 0
	s_nop 0
	s_nop 1
	s_mov_b32 s98, 0x5040100
	s_mov_b32 s100, 0x40000
	s_mov_b32 s101, 0
	v_perm_b32 v214, v32, v0, s98
	v_perm_b32 v215, v34, v33, s98
	v_bfe_i32 v206, v227, 0, 1
	v_and_b32_e32 v206, 0x5050505, v206
	v_xor_b32_e32 v206, 0x6020400, v206
	v_bfe_i32 v207, v227, 1, 1
	v_and_b32_e32 v207, 0x6060606, v207
	v_xor_b32_e32 v207, 0x5040100, v207
	v_mov_b32_dpp v216, v214 quad_perm:[1,0,3,2] row_mask:0xf bank_mask:0xf
	v_mov_b32_dpp v217, v215 quad_perm:[1,0,3,2] row_mask:0xf bank_mask:0xf
	v_and_b32_e32 v220, 3, v227
	v_perm_b32 v214, v216, v214, v206
	v_perm_b32 v215, v217, v215, v206
	v_mul_u32_u24_e32 v220, 0x3fff, v220
	v_mov_b32_e32 v221, 0
	v_mov_b32_dpp v216, v214 quad_perm:[2,3,0,1] row_mask:0xf bank_mask:0xf
	v_mov_b32_dpp v217, v215 quad_perm:[2,3,0,1] row_mask:0xf bank_mask:0xf
	v_lshl_add_u64 v[218:219], v[36:37], 0, v[220:221]
	v_perm_b32 v214, v216, v214, v207
	v_perm_b32 v215, v217, v215, v207
	v_lshl_add_u64 v[220:221], v[218:219], 0, s[100:101]
	global_store_dword v[218:219], v214, off
	global_store_dword v[220:221], v215, off

; DI unsigned pack2(float a, float b) { f2_t v = {a, b}; return __builtin_bit_cast(unsigned, __builtin_convertvector(v, bf2_t)); }
;   DI void operator()(const f32x4 (&acc)[2][2][4][2], const pg8::Unit& u, int wr, int wc, int fr, int fq) const {
;     ...
;           u16* dp = proj + (size_t)row * NPROJ;
;           *(uint2*)(dp + c1) = make_uint2(pack2(x1[0] * scale, x1[1] * scale), pack2(x1[2] * scale, x1[3] * scale));
;           *(uint2*)(dp + c2) = make_uint2(pack2(x2[0] * scale, x2[1] * scale), pack2(x2[2] * scale, x2[3] * scale));
;           if (gcol0 >= 512 && gcol0 < 768) {
;             const int hd = (gcol0 - 512) >> 6, d0 = (gcol0 & 63) + 4 * fq;
;             unsigned char* vp = vt8 + ((size_t)((row >> 14) * 4 + hd) * 64 + d0) * S + (row & (S - 1));
;             const int w1a = __builtin_amdgcn_cvt_pk_fp8_f32(x1[0], x1[1], 0, false), w1b = __builtin_amdgcn_cvt_pk_fp8_f32(x1[2], x1[3], 0, false);
;             const int w2a = __builtin_amdgcn_cvt_pk_fp8_f32(x2[0], x2[1], 0, false), w2b = __builtin_amdgcn_cvt_pk_fp8_f32(x2[2], x2[3], 0, false);
;             vp[0] = (unsigned char)(w1a & 0xff); vp[(size_t)S] = (unsigned char)((w1a >> 8) & 0xff); vp[(size_t)2 * S] = (unsigned char)(w1b & 0xff); vp[(size_t)3 * S] = (unsigned char)((w1b >> 8) & 0xff);
;             unsigned char* vq = vp + (size_t)16 * S;
;             vq[0] = (unsigned char)(w2a & 0xff); vq[(size_t)S] = (unsigned char)((w2a >> 8) & 0xff); vq[(size_t)2 * S] = (unsigned char)(w2b & 0xff); vq[(size_t)3 * S] = (unsigned char)((w2b >> 8) & 0xff);
.LBB0_199:
	v_pk_mul_f32 v[10:11], v[84:85], v[6:7]
	v_pk_mul_f32 v[12:13], v[84:85], v[8:9]
	v_cvt_pk_bf16_f32 v10, v10, v11
	v_cvt_pk_bf16_f32 v11, v12, v13
	v_lshl_add_u64 v[12:13], v[88:89], 1, v[94:95]
	v_mov_b32_e32 v202, v10
	v_mov_b32_e32 v203, v11
	s_nop 1
	v_permlane16_swap_b32_e32 v200, v202
	v_permlane16_swap_b32_e32 v201, v203
	global_store_dwordx4 v[204:205], v[200:203], off
	v_pk_mul_f32 v[10:11], v[84:85], v[2:3]
	v_pk_mul_f32 v[12:13], v[84:85], v[4:5]
	v_cvt_pk_bf16_f32 v10, v10, v11
	v_cvt_pk_bf16_f32 v11, v12, v13
	v_lshl_add_u64 v[12:13], v[86:87], 1, v[94:95]
	s_and_b64 vcc, exec, s[40:41]
	v_mov_b32_e32 v210, v10
	v_mov_b32_e32 v211, v11
	s_nop 1
	v_permlane16_swap_b32_e32 v208, v210
	v_permlane16_swap_b32_e32 v209, v211
	global_store_dwordx4 v[212:213], v[208:211], off
	s_cbranch_vccnz .LBB0_112
	v_mov_b32_e32 v0, v1
	v_cvt_pk_fp8_f32 v0, v6, v7
	v_mov_b32_e32 v93, v1
	v_lshl_add_u64 v[10:11], v[52:53], 0, v[92:93]
	v_mov_b32_e32 v6, v1
	v_mov_b32_e32 v7, v1
	v_cvt_pk_fp8_f32 v6, v8, v9
	v_cvt_pk_fp8_f32 v7, v2, v3
	s_nop 0
	v_mov_b32_e32 v8, v1
	s_nop 0
	v_cvt_pk_fp8_f32 v8, v4, v5
	s_nop 0
	s_nop 0
	s_nop 0
	s_nop 1
	s_mov_b32 s98, 0x5040100
	s_mov_b32 s100, 0x40000
	s_mov_b32 s101, 0
	v_perm_b32 v214, v6, v0, s98
	v_perm_b32 v215, v8, v7, s98
	v_bfe_i32 v206, v227, 0, 1
	v_and_b32_e32 v206, 0x5050505, v206
	v_xor_b32_e32 v206, 0x6020400, v206
	v_bfe_i32 v207, v227, 1, 1
	v_and_b32_e32 v207, 0x6060606, v207
	v_xor_b32_e32 v207, 0x5040100, v207
	v_mov_b32_dpp v216, v214 quad_perm:[1,0,3,2] row_mask:0xf bank_mask:0xf
	v_mov_b32_dpp v217, v215 quad_perm:[1,0,3,2] row_mask:0xf bank_mask:0xf
	v_and_b32_e32 v220, 3, v227
	v_perm_b32 v214, v216, v214, v206
	v_perm_b32 v215, v217, v215, v206
	v_mul_u32_u24_e32 v220, 0x3fff, v220
	v_mov_b32_e32 v221, 0
	v_mov_b32_dpp v216, v214 quad_perm:[2,3,0,1] row_mask:0xf bank_mask:0xf
	v_mov_b32_dpp v217, v215 quad_perm:[2,3,0,1] row_mask:0xf bank_mask:0xf
	v_lshl_add_u64 v[218:219], v[10:11], 0, v[220:221]
	v_perm_b32 v214, v216, v214, v207
	v_perm_b32 v215, v217, v215, v207
	v_lshl_add_u64 v[220:221], v[218:219], 0, s[100:101]
	global_store_dword v[218:219], v214, off
	global_store_dword v[220:221], v215, off
	s_branch .LBB0_112
